# v90 + P6 merge/RMS loop: attn_g/ssm_g weight fragments loaded once before the row loop instead of per row (the prompt path waited for them in a separate round trip)
# speedup vs baseline: 1.0020x; 1.0020x over previous
; __device__ __forceinline__ unsigned pk2(float lo, float hi) { f32x2_t v = {lo, hi}; bf16x2_t b = __builtin_convertvector(v, bf16x2_t); return __builtin_bit_cast(unsigned, b); }
; __device__ __forceinline__ float wsum(float v) { v += __shfl_xor(v, 32); v += __shfl_xor(v, 16); v += __shfl_xor(v, 8); v += __shfl_xor(v, 4); v += __shfl_xor(v, 2); v += __shfl_xor(v, 1); return v; }
; __device__ __forceinline__ void rms_half(const bfu* src, const float* gam, bfu* dst, int lane) {
;     float a[8], c[8];
;     ld8f(src + lane * 8, a); ld8f(src + 512 + lane * 8, c);
;     float ss = 0.f;
; #pragma unroll
;     for (int j = 0; j < 8; ++j) ss += a[j] * a[j] + c[j] * c[j];
;     ss = wsum(ss);
;     const float rs = rsqrtf(ss * (1.f / 1024.f) + EPS);
;     float g0[8], g1[8]; ld8f32(gam + lane * 8, g0); ld8f32(gam + 512 + lane * 8, g1);
;     uint4 o0, o1;
;     o0.x = pk2(a[0] * rs * g0[0], a[1] * rs * g0[1]); o0.y = pk2(a[2] * rs * g0[2], a[3] * rs * g0[3]); o0.z = pk2(a[4] * rs * g0[4], a[5] * rs * g0[5]); o0.w = pk2(a[6] * rs * g0[6], a[7] * rs * g0[7]);
;     o1.x = pk2(c[0] * rs * g1[0], c[1] * rs * g1[1]); o1.y = pk2(c[2] * rs * g1[2], c[3] * rs * g1[3]); o1.z = pk2(c[4] * rs * g1[4], c[5] * rs * g1[5]); o1.w = pk2(c[6] * rs * g1[6], c[7] * rs * g1[7]);
;     *(uint4*)(dst + lane * 8) = o0; *(uint4*)(dst + 512 + lane * 8) = o1;
; }
; __device__ __forceinline__ void phase6(const Params& p, int bid, int G) {
;     const int lane = threadIdx.x & 63, wave = threadIdx.x >> 6;
;     const bfu* att = (const bfu*)(p.ws + WS_ATT); const bfu* yg = (const bfu*)(p.ws + WS_YG); bfu* mix = (bfu*)(p.ws + WS_MIX);
;     for (int row = bid * 8 + wave; row < MT; row += G * 8) {
;         if (row < MP) attn_merge_rms(p, row, mix + (size_t)row * 2048, lane);
;         else rms_half(att + (size_t)row * 1024, p.attn_g, mix + (size_t)row * 2048, lane);
;         rms_half(yg + (size_t)row * 1024, p.ssm_g, mix + (size_t)row * 2048 + 1024, lane);
;     }
; }
.LBB0_601:
	s_or_b64 exec, exec, s[0:1]
	s_lshl_b32 s58, s2, 3
	v_readlane_b32 s8, v252, 1
	v_add_u32_e32 v128, s58, v194
	s_movk_i32 s0, 0x4100
	v_readlane_b32 s9, v252, 2
	v_cmp_gt_i32_e64 s[6:7], s0, v128
	v_ashrrev_i32_e32 v129, 31, v128
	s_waitcnt lgkmcnt(0)
	s_barrier
	s_and_saveexec_b64 s[0:1], s[6:7]
	s_cbranch_execz .LBB0_608
	v_mbcnt_lo_u32_b32 v0, -1, 0
	v_mbcnt_hi_u32_b32 v0, -1, v0
	v_and_b32_e32 v2, 64, v0
	v_xor_b32_e32 v1, 32, v0
	v_add_u32_e32 v2, 64, v2
	v_cmp_lt_i32_e32 vcc, v1, v2
	s_load_dwordx2 s[4:5], s[8:9], 0xb8
	s_load_dwordx4 s[12:15], s[8:9], 0x60
	v_cndmask_b32_e32 v1, v0, v1, vcc
	v_lshlrev_b32_e32 v40, 2, v1
	v_xor_b32_e32 v1, 16, v0
	v_cmp_lt_i32_e32 vcc, v1, v2
	s_mov_b64 s[8:9], 0x1a900000
	s_lshl_b32 s10, s92, 3
	v_cndmask_b32_e32 v1, v0, v1, vcc
	v_lshlrev_b32_e32 v41, 2, v1
	v_xor_b32_e32 v1, 8, v0
	v_cmp_lt_i32_e32 vcc, v1, v2
	s_ashr_i32 s11, s10, 31
	v_lshlrev_b64 v[12:13], 11, v[128:129]
	v_cndmask_b32_e32 v1, v0, v1, vcc
	v_lshlrev_b32_e32 v42, 2, v1
	v_xor_b32_e32 v1, 4, v0
	v_cmp_lt_i32_e32 vcc, v1, v2
	v_lshlrev_b64 v[16:17], 6, v[128:129]
	v_mov_b32_e32 v15, v13
	v_cndmask_b32_e32 v1, v0, v1, vcc
	v_lshlrev_b32_e32 v43, 2, v1
	v_xor_b32_e32 v1, 2, v0
	v_cmp_lt_i32_e32 vcc, v1, v2
	v_and_or_b32 v16, v177, 28, v16
	s_mov_b64 s[16:17], 0
	v_cndmask_b32_e32 v1, v0, v1, vcc
	v_lshlrev_b32_e32 v44, 2, v1
	v_xor_b32_e32 v1, 1, v0
	v_cmp_lt_i32_e32 vcc, v1, v2
	s_movk_i32 s3, 0x3fff
	v_mov_b32_e32 v46, 0x3727c5ac
	v_cndmask_b32_e32 v0, v0, v1, vcc
	v_lshlrev_b32_e32 v45, 2, v0
	v_lshlrev_b32_e32 v0, 5, v179
	v_mov_b32_e32 v1, 0
	s_waitcnt lgkmcnt(0)
	v_lshl_add_u64 v[2:3], s[14:15], 0, v[0:1]
	v_lshl_add_u64 v[4:5], s[12:13], 0, v[0:1]
	v_lshlrev_b32_e32 v0, 4, v179
	v_lshl_add_u64 v[10:11], s[4:5], 0, v[0:1]
	v_lshl_add_u64 v[6:7], v[10:11], 0, s[8:9]
	s_mov_b64 s[8:9], 0x24c00000
	v_lshl_add_u64 v[8:9], v[10:11], 0, s[8:9]
	s_mov_b64 s[8:9], 0x22b00000
	v_lshl_add_u64 v[10:11], v[10:11], 0, s[8:9]
	v_or_b32_e32 v14, v12, v0
	s_lshl_b64 s[12:13], s[10:11], 11
	s_lshl_b64 s[14:15], s[10:11], 6
	s_mov_b32 s20, 0x800000
	s_mov_b32 s21, 0x28d00000
	s_mov_b32 s22, 0x2ad00000
	s_mov_b32 s23, 0x2cd00000
	s_movk_i32 s24, 0x40ff
	v_mov_b64_e32 v[18:19], v[128:129]
	global_load_dwordx4 v[104:107], v[4:5], off offset:2064
	global_load_dwordx4 v[108:111], v[4:5], off offset:2048
	global_load_dwordx4 v[112:115], v[4:5], off offset:16
	global_load_dwordx4 v[116:119], v[4:5], off
	global_load_dwordx4 v[130:133], v[2:3], off offset:2064
	global_load_dwordx4 v[134:137], v[2:3], off offset:2048
	global_load_dwordx4 v[138:141], v[2:3], off offset:16
	global_load_dwordx4 v[142:145], v[2:3], off
	s_branch .LBB0_604
.LBB0_603:
	s_or_b64 exec, exec, s[18:19]
	v_lshlrev_b64 v[38:39], 12, v[38:39]
	v_cvt_pk_bf16_f32 v29, v28, v29
	v_cvt_pk_bf16_f32 v28, v26, v27
	v_cvt_pk_bf16_f32 v27, v24, v25
	v_cvt_pk_bf16_f32 v26, v22, v23
	v_lshl_add_u64 v[52:53], v[8:9], 0, v[38:39]
	v_cvt_pk_bf16_f32 v36, v36, v37
	v_cvt_pk_bf16_f32 v35, v34, v35
	v_cvt_pk_bf16_f32 v34, v32, v33
	v_cvt_pk_bf16_f32 v37, v30, v31
	global_store_dwordx4 v[52:53], v[26:29], off
	global_store_dwordx4 v[52:53], v[34:37], off offset:1024
	v_lshl_add_u64 v[54:55], v[10:11], 0, v[20:21]
	global_load_dwordx4 v[20:23], v[54:55], off
	global_load_dwordx4 v[24:27], v[54:55], off offset:1024
	v_lshl_add_u64 v[18:19], v[18:19], 0, s[10:11]
	v_cmp_lt_i32_e64 s[8:9], s24, v18
	v_lshl_add_u64 v[14:15], v[14:15], 0, s[12:13]
	v_lshl_add_u64 v[12:13], v[12:13], 0, s[12:13]
	s_or_b64 s[16:17], s[8:9], s[16:17]
	v_lshl_add_u64 v[16:17], v[16:17], 0, s[14:15]
	s_waitcnt vmcnt(1)
	v_lshlrev_b32_e32 v54, 16, v20
	s_waitcnt vmcnt(0)
	v_lshlrev_b32_e32 v58, 16, v24
	v_and_b32_e32 v59, 0xffff0000, v24
	v_and_b32_e32 v55, 0xffff0000, v20
	v_lshlrev_b32_e32 v24, 16, v25
	v_and_b32_e32 v25, 0xffff0000, v25
	v_pk_mul_f32 v[64:65], v[58:59], v[58:59]
	v_lshlrev_b32_e32 v20, 16, v21
	v_and_b32_e32 v21, 0xffff0000, v21
	v_pk_mul_f32 v[62:63], v[24:25], v[24:25]
	v_pk_fma_f32 v[64:65], v[54:55], v[54:55], v[64:65]
	v_lshlrev_b32_e32 v60, 16, v26
	v_and_b32_e32 v61, 0xffff0000, v26
	v_pk_fma_f32 v[62:63], v[20:21], v[20:21], v[62:63]
	v_add_f32_e32 v0, v64, v65
	v_lshlrev_b32_e32 v56, 16, v22
	v_and_b32_e32 v57, 0xffff0000, v22
	v_pk_mul_f32 v[68:69], v[60:61], v[60:61]
	v_add_f32_e32 v0, v0, v62
	v_lshlrev_b32_e32 v26, 16, v27
	v_and_b32_e32 v27, 0xffff0000, v27
	v_pk_fma_f32 v[68:69], v[56:57], v[56:57], v[68:69]
	v_add_f32_e32 v0, v63, v0
	v_lshlrev_b32_e32 v22, 16, v23
	v_and_b32_e32 v23, 0xffff0000, v23
	v_pk_mul_f32 v[66:67], v[26:27], v[26:27]
	v_add_f32_e32 v0, v68, v0
	v_pk_fma_f32 v[66:67], v[22:23], v[22:23], v[66:67]
	v_add_f32_e32 v0, v69, v0
	v_add_f32_e32 v0, v66, v0
	v_add_f32_e32 v0, v67, v0
	ds_bpermute_b32 v47, v40, v0
	s_waitcnt lgkmcnt(0)
	v_add_f32_e32 v0, v0, v47
	ds_bpermute_b32 v47, v41, v0
	s_waitcnt lgkmcnt(0)
	v_add_f32_e32 v0, v0, v47
	ds_bpermute_b32 v47, v42, v0
	s_waitcnt lgkmcnt(0)
	v_add_f32_e32 v0, v0, v47
	ds_bpermute_b32 v47, v43, v0
	s_waitcnt lgkmcnt(0)
	v_add_f32_e32 v0, v0, v47
	ds_bpermute_b32 v47, v44, v0
	s_waitcnt lgkmcnt(0)
	v_add_f32_e32 v0, v0, v47
	ds_bpermute_b32 v47, v45, v0
	s_waitcnt lgkmcnt(0)
	v_add_f32_e32 v0, v0, v47
	v_fmamk_f32 v0, v0, 0x3a800000, v46
	v_mul_f32_e32 v47, 0x4b800000, v0
	v_cmp_gt_f32_e32 vcc, s20, v0
	s_nop 1
	v_cndmask_b32_e32 v0, v0, v47, vcc
	v_rsq_f32_e32 v0, v0
	s_nop 0
	v_mul_f32_e32 v47, 0x45800000, v0
	v_cndmask_b32_e32 v0, v0, v47, vcc
	v_pk_mul_f32 v[54:55], v[0:1], v[54:55] op_sel_hi:[0,1]
	v_pk_mul_f32 v[20:21], v[0:1], v[20:21] op_sel_hi:[0,1]
	v_pk_mul_f32 v[56:57], v[0:1], v[56:57] op_sel_hi:[0,1]
	v_pk_mul_f32 v[22:23], v[0:1], v[22:23] op_sel_hi:[0,1]
	v_pk_mul_f32 v[58:59], v[0:1], v[58:59] op_sel_hi:[0,1]
	v_pk_mul_f32 v[24:25], v[0:1], v[24:25] op_sel_hi:[0,1]
	v_pk_mul_f32 v[60:61], v[0:1], v[60:61] op_sel_hi:[0,1]
	v_pk_mul_f32 v[26:27], v[0:1], v[26:27] op_sel_hi:[0,1]
	s_waitcnt vmcnt(0)
	v_mov_b64_e32 v[28:29], v[130:131]
	v_mov_b64_e32 v[30:31], v[132:133]
	v_mov_b64_e32 v[32:33], v[134:135]
	v_mov_b64_e32 v[34:35], v[136:137]
	v_mov_b64_e32 v[36:37], v[138:139]
	v_mov_b64_e32 v[38:39], v[140:141]
	v_mov_b64_e32 v[48:49], v[142:143]
	v_mov_b64_e32 v[50:51], v[144:145]
	v_pk_mul_f32 v[48:49], v[48:49], v[54:55]
	v_pk_mul_f32 v[50:51], v[50:51], v[20:21]
	v_pk_mul_f32 v[36:37], v[36:37], v[56:57]
	v_pk_mul_f32 v[38:39], v[38:39], v[22:23]
	v_pk_mul_f32 v[32:33], v[32:33], v[58:59]
	v_pk_mul_f32 v[34:35], v[34:35], v[24:25]
	v_pk_mul_f32 v[28:29], v[28:29], v[60:61]
	v_pk_mul_f32 v[30:31], v[30:31], v[26:27]
	v_cvt_pk_bf16_f32 v20, v48, v49
	v_cvt_pk_bf16_f32 v21, v50, v51
	v_cvt_pk_bf16_f32 v22, v36, v37
	v_cvt_pk_bf16_f32 v23, v38, v39
	v_cvt_pk_bf16_f32 v24, v32, v33
	v_cvt_pk_bf16_f32 v25, v34, v35
	v_cvt_pk_bf16_f32 v26, v28, v29
	v_cvt_pk_bf16_f32 v27, v30, v31
	global_store_dwordx4 v[52:53], v[20:23], off offset:2048
	global_store_dwordx4 v[52:53], v[24:27], off offset:3072
	s_andn2_b64 exec, exec, s[16:17]
	s_cbranch_execz .LBB0_608
; __device__ __forceinline__ unsigned pk2(float lo, float hi) { f32x2_t v = {lo, hi}; bf16x2_t b = __builtin_convertvector(v, bf16x2_t); return __builtin_bit_cast(unsigned, b); }
; __device__ __forceinline__ void rms_half(const bfu* src, const float* gam, bfu* dst, int lane) {
;     float a[8], c[8];
;     ld8f(src + lane * 8, a); ld8f(src + 512 + lane * 8, c);
;     float ss = 0.f;
; #pragma unroll
;     for (int j = 0; j < 8; ++j) ss += a[j] * a[j] + c[j] * c[j];
;     ss = wsum(ss);
;     const float rs = rsqrtf(ss * (1.f / 1024.f) + EPS);
;     float g0[8], g1[8]; ld8f32(gam + lane * 8, g0); ld8f32(gam + 512 + lane * 8, g1);
;     uint4 o0, o1;
;     o0.x = pk2(a[0] * rs * g0[0], a[1] * rs * g0[1]); o0.y = pk2(a[2] * rs * g0[2], a[3] * rs * g0[3]); o0.z = pk2(a[4] * rs * g0[4], a[5] * rs * g0[5]); o0.w = pk2(a[6] * rs * g0[6], a[7] * rs * g0[7]);
;     o1.x = pk2(c[0] * rs * g1[0], c[1] * rs * g1[1]); o1.y = pk2(c[2] * rs * g1[2], c[3] * rs * g1[3]); o1.z = pk2(c[4] * rs * g1[4], c[5] * rs * g1[5]); o1.w = pk2(c[6] * rs * g1[6], c[7] * rs * g1[7]);
;     *(uint4*)(dst + lane * 8) = o0; *(uint4*)(dst + 512 + lane * 8) = o1;
; }
; __device__ __forceinline__ void attn_merge_rms(const Params& p, int row, bfu* dst, int lane) {
;     const bfu* attb = (const bfu*)(p.ws + WS_ATTB); const float* lse = (const float*)(p.ws + WS_LSE);
;     float a[8], c[8];
; #pragma unroll
;     for (int j = 0; j < 8; ++j) { a[j] = 0.f; c[j] = 0.f; }
;     const int h0 = lane >> 3, h1 = 8 + (lane >> 3);
;     float l0[3], l1[3];
; #pragma unroll
;     for (int br = 0; br < 3; ++br) { l0[br] = lse[(size_t)br * (MP * 16) + (size_t)row * 16 + h0]; l1[br] = lse[(size_t)br * (MP * 16) + (size_t)row * 16 + h1]; }
;     const float m0 = fmaxf(fmaxf(l0[0], l0[1]), l0[2]), m1 = fmaxf(fmaxf(l1[0], l1[1]), l1[2]);
;     float w0[3], w1[3];
; #pragma unroll
;     for (int br = 0; br < 3; ++br) { w0[br] = __expf(l0[br] - m0); w1[br] = __expf(l1[br] - m1); }
;     const float i0 = 1.f / (w0[0] + w0[1] + w0[2]), i1 = 1.f / (w1[0] + w1[1] + w1[2]);
; #pragma unroll
;     for (int br = 0; br < 3; ++br) {
;         float x[8], y[8];
;         const bfu* src = attb + (size_t)br * ((size_t)MP * 1024) + (size_t)row * 1024;
;         ld8f(src + lane * 8, x); ld8f(src + 512 + lane * 8, y);
.LBB0_604:
	v_cmp_lt_i32_e32 vcc, s3, v18
	s_and_saveexec_b64 s[8:9], vcc
	s_xor_b64 s[8:9], exec, s[8:9]
	s_cbranch_execz .LBB0_606
	v_mov_b32_e32 v0, v18
	v_lshlrev_b64 v[20:21], 11, v[0:1]
	v_lshl_add_u64 v[30:31], v[6:7], 0, v[20:21]
	global_load_dwordx4 v[22:25], v[30:31], off
	global_load_dwordx4 v[26:29], v[30:31], off offset:1024
	s_waitcnt vmcnt(1)
	v_lshlrev_b32_e32 v30, 16, v22
	s_waitcnt vmcnt(0)
	v_lshlrev_b32_e32 v58, 16, v26
	v_and_b32_e32 v59, 0xffff0000, v26
	v_and_b32_e32 v31, 0xffff0000, v22
	v_lshlrev_b32_e32 v26, 16, v27
	v_and_b32_e32 v27, 0xffff0000, v27
	v_pk_mul_f32 v[64:65], v[58:59], v[58:59]
	v_lshlrev_b32_e32 v22, 16, v23
	v_and_b32_e32 v23, 0xffff0000, v23
	v_pk_mul_f32 v[62:63], v[26:27], v[26:27]
	v_pk_fma_f32 v[64:65], v[30:31], v[30:31], v[64:65]
	v_lshlrev_b32_e32 v60, 16, v28
	v_and_b32_e32 v61, 0xffff0000, v28
	v_pk_fma_f32 v[62:63], v[22:23], v[22:23], v[62:63]
	v_add_f32_e32 v47, v64, v65
	v_lshlrev_b32_e32 v56, 16, v24
	v_and_b32_e32 v57, 0xffff0000, v24
	v_pk_mul_f32 v[68:69], v[60:61], v[60:61]
	v_add_f32_e32 v47, v47, v62
	v_lshlrev_b32_e32 v28, 16, v29
	v_and_b32_e32 v29, 0xffff0000, v29
	v_pk_fma_f32 v[68:69], v[56:57], v[56:57], v[68:69]
	v_add_f32_e32 v47, v63, v47
	v_lshlrev_b32_e32 v24, 16, v25
	v_and_b32_e32 v25, 0xffff0000, v25
	v_pk_mul_f32 v[66:67], v[28:29], v[28:29]
	v_add_f32_e32 v47, v68, v47
	v_pk_fma_f32 v[66:67], v[24:25], v[24:25], v[66:67]
	v_add_f32_e32 v47, v69, v47
	v_add_f32_e32 v47, v66, v47
	v_add_f32_e32 v47, v67, v47
	ds_bpermute_b32 v62, v40, v47
	s_waitcnt lgkmcnt(0)
	v_add_f32_e32 v47, v47, v62
	ds_bpermute_b32 v62, v41, v47
	s_waitcnt lgkmcnt(0)
	v_add_f32_e32 v47, v47, v62
	ds_bpermute_b32 v62, v42, v47
	s_waitcnt lgkmcnt(0)
	v_add_f32_e32 v47, v47, v62
	ds_bpermute_b32 v62, v43, v47
	s_waitcnt lgkmcnt(0)
	v_add_f32_e32 v47, v47, v62
	ds_bpermute_b32 v62, v44, v47
	s_waitcnt lgkmcnt(0)
	v_add_f32_e32 v47, v47, v62
	ds_bpermute_b32 v62, v45, v47
	s_waitcnt lgkmcnt(0)
	v_add_f32_e32 v47, v47, v62
	v_fmamk_f32 v47, v47, 0x3a800000, v46
	v_mul_f32_e32 v62, 0x4b800000, v47
	v_cmp_gt_f32_e32 vcc, s20, v47
	s_nop 1
	v_cndmask_b32_e32 v47, v47, v62, vcc
	v_rsq_f32_e32 v47, v47
	s_nop 0
	v_mul_f32_e32 v62, 0x45800000, v47
	v_cndmask_b32_e32 v62, v47, v62, vcc
	v_pk_mul_f32 v[30:31], v[62:63], v[30:31] op_sel_hi:[0,1]
	v_pk_mul_f32 v[64:65], v[62:63], v[22:23] op_sel_hi:[0,1]
	v_pk_mul_f32 v[56:57], v[62:63], v[56:57] op_sel_hi:[0,1]
	v_pk_mul_f32 v[66:67], v[62:63], v[24:25] op_sel_hi:[0,1]
	v_pk_mul_f32 v[58:59], v[62:63], v[58:59] op_sel_hi:[0,1]
	v_pk_mul_f32 v[68:69], v[62:63], v[26:27] op_sel_hi:[0,1]
	v_pk_mul_f32 v[60:61], v[62:63], v[60:61] op_sel_hi:[0,1]
	v_pk_mul_f32 v[62:63], v[62:63], v[28:29] op_sel_hi:[0,1]
	s_waitcnt vmcnt(0)
	v_mov_b64_e32 v[36:37], v[104:105]
	v_mov_b64_e32 v[38:39], v[106:107]
	v_mov_b64_e32 v[32:33], v[108:109]
	v_mov_b64_e32 v[34:35], v[110:111]
	v_mov_b64_e32 v[48:49], v[112:113]
	v_mov_b64_e32 v[50:51], v[114:115]
	v_mov_b64_e32 v[52:53], v[116:117]
	v_mov_b64_e32 v[54:55], v[118:119]
	v_pk_mul_f32 v[22:23], v[52:53], v[30:31]
	v_pk_mul_f32 v[24:25], v[54:55], v[64:65]
	v_pk_mul_f32 v[26:27], v[48:49], v[56:57]
	v_pk_mul_f32 v[28:29], v[50:51], v[66:67]
	v_pk_mul_f32 v[32:33], v[32:33], v[58:59]
	v_pk_mul_f32 v[34:35], v[34:35], v[68:69]
	v_pk_mul_f32 v[36:37], v[36:37], v[60:61]
	v_pk_mul_f32 v[30:31], v[38:39], v[62:63]
	v_mov_b64_e32 v[38:39], v[0:1]
.LBB0_606:
	s_andn2_saveexec_b64 s[18:19], s[8:9]
	s_cbranch_execz .LBB0_603
	v_lshl_add_u64 v[28:29], s[4:5], 0, v[16:17]
	v_add_co_u32_e32 v30, vcc, 0x30f00000, v28
	v_lshl_add_u64 v[36:37], s[4:5], 0, v[14:15]
	s_nop 0
	v_addc_co_u32_e32 v31, vcc, 0, v29, vcc
	v_add_co_u32_e32 v24, vcc, s21, v36
	s_nop 1
	v_addc_co_u32_e32 v25, vcc, 0, v37, vcc
	v_add_co_u32_e32 v32, vcc, 0x31000000, v28
	global_load_dwordx4 v[20:23], v[24:25], off
	s_nop 0
	v_addc_co_u32_e32 v33, vcc, 0, v29, vcc
	v_add_co_u32_e32 v28, vcc, 0x31100000, v28
	global_load_dwordx4 v[24:27], v[24:25], off offset:1024
	s_nop 0
	v_addc_co_u32_e32 v29, vcc, 0, v29, vcc
	global_load_dword v0, v[30:31], off
	global_load_dword v47, v[30:31], off offset:32
	global_load_dword v60, v[32:33], off
	global_load_dword v61, v[32:33], off offset:32
	global_load_dword v62, v[28:29], off
	global_load_dword v63, v[28:29], off offset:32
	v_add_co_u32_e32 v38, vcc, s22, v36
	s_waitcnt vmcnt(7)
	v_lshlrev_b32_e32 v54, 16, v22
	v_addc_co_u32_e32 v39, vcc, 0, v37, vcc
	v_add_co_u32_e32 v52, vcc, s23, v36
	global_load_dwordx4 v[28:31], v[38:39], off
	global_load_dwordx4 v[32:35], v[38:39], off offset:1024
	v_addc_co_u32_e32 v53, vcc, 0, v37, vcc
	global_load_dwordx4 v[36:39], v[52:53], off
	global_load_dwordx4 v[48:51], v[52:53], off offset:1024
	s_waitcnt vmcnt(5)
	v_max3_f32 v64, v0, v60, v62
	s_waitcnt vmcnt(4)
; __device__ __forceinline__ void attn_merge_rms(const Params& p, int row, bfu* dst, int lane) {
;     ...
;     for (int br = 0; br < 3; ++br) { l0[br] = lse[(size_t)br * (MP * 16) + (size_t)row * 16 + h0]; l1[br] = lse[(size_t)br * (MP * 16) + (size_t)row * 16 + h1]; }
;     const float m0 = fmaxf(fmaxf(l0[0], l0[1]), l0[2]), m1 = fmaxf(fmaxf(l1[0], l1[1]), l1[2]);
;     float w0[3], w1[3];
; #pragma unroll
;     for (int br = 0; br < 3; ++br) { w0[br] = __expf(l0[br] - m0); w1[br] = __expf(l1[br] - m1); }
;     const float i0 = 1.f / (w0[0] + w0[1] + w0[2]), i1 = 1.f / (w1[0] + w1[1] + w1[2]);
; #pragma unroll
;     for (int br = 0; br < 3; ++br) {
;         float x[8], y[8];
;         const bfu* src = attb + (size_t)br * ((size_t)MP * 1024) + (size_t)row * 1024;
;         ld8f(src + lane * 8, x); ld8f(src + 512 + lane * 8, y);
;         const float f0 = w0[br] * i0, f1 = w1[br] * i1;
; #pragma unroll
;         for (int j = 0; j < 8; ++j) { a[j] += f0 * x[j]; c[j] += f1 * y[j]; }
	v_max3_f32 v65, v47, v61, v63
	v_sub_f32_e32 v0, v0, v64
	v_sub_f32_e32 v60, v60, v64
	v_sub_f32_e32 v47, v47, v65
	v_sub_f32_e32 v61, v61, v65
	v_sub_f32_e32 v62, v62, v64
	v_mul_f32_e32 v0, 0x3fb8aa3b, v0
	v_mul_f32_e32 v60, 0x3fb8aa3b, v60
	v_sub_f32_e32 v63, v63, v65
	v_mul_f32_e32 v47, 0x3fb8aa3b, v47
	v_mul_f32_e32 v61, 0x3fb8aa3b, v61
	v_mul_f32_e32 v64, 0x3fb8aa3b, v62
	v_exp_f32_e32 v65, v0
	v_exp_f32_e32 v60, v60
	v_mul_f32_e32 v63, 0x3fb8aa3b, v63
	v_exp_f32_e32 v47, v47
	v_exp_f32_e32 v62, v61
	v_exp_f32_e32 v61, v64
	v_exp_f32_e32 v63, v63
	v_add_f32_e32 v0, v65, v60
	v_add_f32_e32 v64, v47, v62
	v_add_f32_e32 v0, v61, v0
	v_add_f32_e32 v64, v63, v64
	v_div_scale_f32 v66, s[8:9], v0, v0, 1.0
	v_div_scale_f32 v68, s[8:9], v64, v64, 1.0
	v_rcp_f32_e32 v69, v66
	v_rcp_f32_e32 v70, v68
	v_div_scale_f32 v67, vcc, 1.0, v0, 1.0
	v_fma_f32 v72, -v66, v69, 1.0
	v_fma_f32 v73, -v68, v70, 1.0
	v_fmac_f32_e32 v69, v72, v69
	v_div_scale_f32 v71, s[8:9], 1.0, v64, 1.0
	v_fmac_f32_e32 v70, v73, v70
	v_mul_f32_e32 v72, v67, v69
	v_mul_f32_e32 v73, v71, v70
	v_fma_f32 v74, -v66, v72, v67
	v_fma_f32 v75, -v68, v73, v71
	v_fmac_f32_e32 v72, v74, v69
	v_fmac_f32_e32 v73, v75, v70
	v_fma_f32 v66, -v66, v72, v67
	v_fma_f32 v67, -v68, v73, v71
	v_div_fmas_f32 v66, v66, v69, v72
	s_mov_b64 vcc, s[8:9]
	v_div_fixup_f32 v0, v66, v0, 1.0
	v_div_fmas_f32 v66, v67, v70, v73
	v_div_fixup_f32 v64, v66, v64, 1.0
	v_mul_f32_e32 v66, v65, v0
	v_pk_mul_f32 v[60:61], v[60:61], v[0:1] op_sel_hi:[1,0]
	v_lshlrev_b32_e32 v56, 16, v24
	v_and_b32_e32 v57, 0xffff0000, v24
	v_lshlrev_b32_e32 v24, 16, v25
	v_and_b32_e32 v25, 0xffff0000, v25
	v_lshlrev_b32_e32 v58, 16, v26
	v_and_b32_e32 v59, 0xffff0000, v26
	v_lshlrev_b32_e32 v26, 16, v27
	v_and_b32_e32 v27, 0xffff0000, v27
	v_mul_f32_e32 v68, v47, v64
	v_and_b32_e32 v55, 0xffff0000, v22
	v_lshlrev_b32_e32 v22, 16, v23
	v_and_b32_e32 v23, 0xffff0000, v23
	v_lshlrev_b32_e32 v52, 16, v20
	v_and_b32_e32 v53, 0xffff0000, v20
	v_lshlrev_b32_e32 v20, 16, v21
	v_and_b32_e32 v21, 0xffff0000, v21
	s_waitcnt vmcnt(3)
	v_lshlrev_b32_e32 v65, 16, v29
	s_waitcnt vmcnt(2)
	v_lshlrev_b32_e32 v70, 16, v35
	v_and_b32_e32 v71, 0xffff0000, v35
	s_waitcnt vmcnt(1)
	v_lshlrev_b32_e32 v35, 16, v36
	v_lshlrev_b32_e32 v83, 16, v37
	v_and_b32_e32 v77, 0xffff0000, v36
	v_and_b32_e32 v37, 0xffff0000, v37
	v_and_b32_e32 v36, 0xffff0000, v29
	v_pk_mul_f32 v[62:63], v[62:63], v[64:65] op_sel_hi:[1,0]
	v_pk_mul_f32 v[94:95], v[60:61], v[36:37]
	s_waitcnt vmcnt(0)
; __device__ __forceinline__ unsigned pk2(float lo, float hi) { f32x2_t v = {lo, hi}; bf16x2_t b = __builtin_convertvector(v, bf16x2_t); return __builtin_bit_cast(unsigned, b); }
; __device__ __forceinline__ float wsum(float v) { v += __shfl_xor(v, 32); v += __shfl_xor(v, 16); v += __shfl_xor(v, 8); v += __shfl_xor(v, 4); v += __shfl_xor(v, 2); v += __shfl_xor(v, 1); return v; }
; __device__ __forceinline__ void attn_merge_rms(const Params& p, int row, bfu* dst, int lane) {
;     ...
;     for (int br = 0; br < 3; ++br) {
;         float x[8], y[8];
;         const bfu* src = attb + (size_t)br * ((size_t)MP * 1024) + (size_t)row * 1024;
;         ld8f(src + lane * 8, x); ld8f(src + 512 + lane * 8, y);
;         const float f0 = w0[br] * i0, f1 = w1[br] * i1;
; #pragma unroll
;         for (int j = 0; j < 8; ++j) { a[j] += f0 * x[j]; c[j] += f1 * y[j]; }
;     }
;     float ss = 0.f;
; #pragma unroll
;     for (int j = 0; j < 8; ++j) ss += a[j] * a[j] + c[j] * c[j];
;     ss = wsum(ss);
;     const float rs = rsqrtf(ss * (1.f / 1024.f) + EPS);
;     const float* gam = p.attn_g;
;     float g0[8], g1[8]; ld8f32(gam + lane * 8, g0); ld8f32(gam + 512 + lane * 8, g1);
;     uint4 o0, o1;
;     o0.x = pk2(a[0] * rs * g0[0], a[1] * rs * g0[1]); o0.y = pk2(a[2] * rs * g0[2], a[3] * rs * g0[3]); o0.z = pk2(a[4] * rs * g0[4], a[5] * rs * g0[5]); o0.w = pk2(a[6] * rs * g0[6], a[7] * rs * g0[7]);
;     o1.x = pk2(c[0] * rs * g1[0], c[1] * rs * g1[1]); o1.y = pk2(c[2] * rs * g1[2], c[3] * rs * g1[3]); o1.z = pk2(c[4] * rs * g1[4], c[5] * rs * g1[5]); o1.w = pk2(c[6] * rs * g1[6], c[7] * rs * g1[7]);
;     *(uint4*)(dst + lane * 8) = o0; *(uint4*)(dst + 512 + lane * 8) = o1;
	v_and_b32_e32 v37, 0xffff0000, v49
	v_and_b32_e32 v36, 0xffff0000, v33
	v_lshlrev_b32_e32 v69, 16, v31
	v_lshlrev_b32_e32 v75, 16, v32
	v_lshlrev_b32_e32 v79, 16, v33
	v_and_b32_e32 v64, 0xffff0000, v32
	v_pk_mul_f32 v[96:97], v[62:63], v[36:37]
	v_and_b32_e32 v33, 0xffff0000, v38
	v_and_b32_e32 v32, 0xffff0000, v30
	v_lshlrev_b32_e32 v88, 16, v48
	v_lshlrev_b32_e32 v89, 16, v49
	v_mul_f32_e32 v78, v60, v65
	v_and_b32_e32 v65, 0xffff0000, v48
	v_mul_f32_e32 v48, v62, v79
	v_pk_mul_f32 v[102:103], v[60:61], v[32:33]
	v_and_b32_e32 v33, 0xffff0000, v50
	v_and_b32_e32 v32, 0xffff0000, v34
	v_pk_fma_f32 v[26:27], v[68:69], v[26:27], 0 op_sel_hi:[0,1,0]
	v_pk_fma_f32 v[24:25], v[68:69], v[24:25], 0 op_sel_hi:[0,1,0]
	v_mov_b32_e32 v49, v96
	v_lshlrev_b32_e32 v81, 16, v34
	v_lshlrev_b32_e32 v87, 16, v39
	v_lshlrev_b32_e32 v91, 16, v50
	v_lshlrev_b32_e32 v72, 16, v51
	v_and_b32_e32 v73, 0xffff0000, v51
	v_pk_mul_f32 v[64:65], v[62:63], v[64:65]
	v_mul_f32_e32 v92, v63, v89
	v_pk_mul_f32 v[50:51], v[62:63], v[32:33]
	v_pk_fma_f32 v[26:27], v[62:63], v[70:71], v[26:27] op_sel_hi:[0,1,1]
	v_pk_add_f32 v[24:25], v[24:25], v[48:49]
	v_mov_b32_e32 v93, v97
	v_lshlrev_b32_e32 v47, 16, v28
	v_lshlrev_b32_e32 v67, 16, v30
	v_and_b32_e32 v76, 0xffff0000, v28
	v_mul_f32_e32 v28, v62, v75
	v_mul_f32_e32 v86, v62, v81
	v_mul_f32_e32 v88, v63, v88
	v_mul_f32_e32 v100, v63, v91
	v_mul_f32_e32 v30, v61, v87
	v_pk_fma_f32 v[62:63], v[62:63], v[72:73], v[26:27] op_sel:[1,0,0]
	v_pk_fma_f32 v[26:27], v[68:69], v[58:59], 0 op_sel_hi:[0,1,0]
	v_mov_b32_e32 v87, v50
	v_pk_add_f32 v[48:49], v[24:25], v[92:93]
	v_pk_fma_f32 v[24:25], v[68:69], v[56:57], 0 op_sel_hi:[0,1,0]
	v_mov_b32_e32 v29, v64
	v_lshlrev_b32_e32 v85, 16, v38
	v_and_b32_e32 v33, 0xffff0000, v39
	v_and_b32_e32 v32, 0xffff0000, v31
	v_pk_add_f32 v[26:27], v[26:27], v[86:87]
	v_mov_b32_e32 v101, v51
	v_pk_add_f32 v[24:25], v[24:25], v[28:29]
	v_mov_b32_e32 v89, v65
	v_mul_f32_e32 v74, v60, v47
	v_pk_mul_f32 v[76:77], v[60:61], v[76:77]
	v_mul_f32_e32 v80, v60, v67
	v_mul_f32_e32 v82, v60, v69
	v_mul_f32_e32 v84, v61, v35
	v_mul_f32_e32 v90, v61, v83
	v_mul_f32_e32 v98, v61, v85
	v_pk_mul_f32 v[60:61], v[60:61], v[32:33]
	v_pk_add_f32 v[50:51], v[26:27], v[100:101]
	v_pk_add_f32 v[56:57], v[24:25], v[88:89]
	v_pk_fma_f32 v[68:69], v[66:67], v[22:23], 0 op_sel_hi:[0,1,0]
	v_pk_fma_f32 v[52:53], v[66:67], v[52:53], 0 op_sel_hi:[0,1,0]
	v_mov_b32_e32 v75, v76
	v_pk_fma_f32 v[20:21], v[66:67], v[20:21], 0 op_sel_hi:[0,1,0]
	v_mov_b32_e32 v79, v94
	v_pk_add_f32 v[52:53], v[52:53], v[74:75]
	v_mov_b32_e32 v85, v77
	v_pk_mul_f32 v[64:65], v[56:57], v[56:57]
	v_pk_add_f32 v[20:21], v[20:21], v[78:79]
	v_mov_b32_e32 v91, v95
	v_pk_add_f32 v[52:53], v[52:53], v[84:85]
	v_pk_mul_f32 v[58:59], v[48:49], v[48:49]
	v_mov_b32_e32 v83, v60
	v_pk_fma_f32 v[54:55], v[66:67], v[54:55], 0 op_sel_hi:[0,1,0]
	v_mov_b32_e32 v81, v102
	v_pk_add_f32 v[20:21], v[20:21], v[90:91]
	v_pk_fma_f32 v[64:65], v[52:53], v[52:53], v[64:65]
	v_pk_add_f32 v[68:69], v[68:69], v[82:83]
	v_mov_b32_e32 v31, v61
	v_pk_add_f32 v[54:55], v[54:55], v[80:81]
	v_mov_b32_e32 v99, v103
	v_pk_fma_f32 v[58:59], v[20:21], v[20:21], v[58:59]
	v_add_f32_e32 v0, v64, v65
	v_pk_add_f32 v[30:31], v[68:69], v[30:31]
	v_pk_add_f32 v[54:55], v[54:55], v[98:99]
	v_pk_mul_f32 v[68:69], v[50:51], v[50:51]
	v_add_f32_e32 v0, v0, v58
	v_pk_fma_f32 v[68:69], v[54:55], v[54:55], v[68:69]
	v_add_f32_e32 v0, v59, v0
	v_pk_mul_f32 v[60:61], v[62:63], v[62:63]
	v_add_f32_e32 v0, v68, v0
	v_pk_fma_f32 v[60:61], v[30:31], v[30:31], v[60:61]
	v_add_f32_e32 v0, v69, v0
	v_add_f32_e32 v0, v60, v0
	v_add_f32_e32 v0, v61, v0
	ds_bpermute_b32 v47, v40, v0
	s_waitcnt lgkmcnt(0)
	v_add_f32_e32 v0, v0, v47
	ds_bpermute_b32 v47, v41, v0
	s_waitcnt lgkmcnt(0)
	v_add_f32_e32 v0, v0, v47
	ds_bpermute_b32 v47, v42, v0
	s_waitcnt lgkmcnt(0)
	v_add_f32_e32 v0, v0, v47
	ds_bpermute_b32 v47, v43, v0
	s_waitcnt lgkmcnt(0)
	v_add_f32_e32 v0, v0, v47
	ds_bpermute_b32 v47, v44, v0
	s_waitcnt lgkmcnt(0)
	v_add_f32_e32 v0, v0, v47
	ds_bpermute_b32 v47, v45, v0
	s_waitcnt lgkmcnt(0)
	v_add_f32_e32 v0, v0, v47
	v_fmamk_f32 v0, v0, 0x3a800000, v46
	v_mul_f32_e32 v47, 0x4b800000, v0
	v_cmp_gt_f32_e32 vcc, s20, v0
	s_nop 1
	v_cndmask_b32_e32 v0, v0, v47, vcc
	v_rsq_f32_e32 v0, v0
	s_nop 0
	v_mul_f32_e32 v47, 0x45800000, v0
	v_cndmask_b32_e32 v0, v0, v47, vcc
	v_pk_mul_f32 v[20:21], v[20:21], v[0:1] op_sel_hi:[1,0]
	v_pk_mul_f32 v[52:53], v[52:53], v[0:1] op_sel_hi:[1,0]
	s_waitcnt vmcnt(0)
	v_mov_b64_e32 v[36:37], v[104:105]
	v_mov_b64_e32 v[38:39], v[106:107]
	v_mov_b64_e32 v[32:33], v[108:109]
	v_mov_b64_e32 v[34:35], v[110:111]
	v_mov_b64_e32 v[26:27], v[112:113]
	v_mov_b64_e32 v[28:29], v[114:115]
	v_mov_b64_e32 v[22:23], v[116:117]
	v_mov_b64_e32 v[24:25], v[118:119]
	v_pk_mul_f32 v[24:25], v[24:25], v[20:21]
	v_pk_mul_f32 v[20:21], v[54:55], v[0:1] op_sel_hi:[1,0]
	v_pk_mul_f32 v[22:23], v[22:23], v[52:53]
	v_pk_mul_f32 v[26:27], v[26:27], v[20:21]
	v_pk_mul_f32 v[20:21], v[30:31], v[0:1] op_sel_hi:[1,0]
	s_nop 0
	v_pk_mul_f32 v[28:29], v[28:29], v[20:21]
	v_pk_mul_f32 v[20:21], v[56:57], v[0:1] op_sel_hi:[1,0]
	s_nop 0
	v_pk_mul_f32 v[32:33], v[32:33], v[20:21]
	v_pk_mul_f32 v[20:21], v[48:49], v[0:1] op_sel_hi:[1,0]
	s_nop 0
	v_pk_mul_f32 v[34:35], v[34:35], v[20:21]
	v_pk_mul_f32 v[20:21], v[50:51], v[0:1] op_sel_hi:[1,0]
	s_nop 0
	v_pk_mul_f32 v[36:37], v[36:37], v[20:21]
	v_pk_mul_f32 v[20:21], v[62:63], v[0:1] op_sel_hi:[1,0]
	s_nop 0
	v_pk_mul_f32 v[30:31], v[38:39], v[20:21]
	v_mov_b64_e32 v[38:39], v[18:19]
	v_mov_b64_e32 v[20:21], v[12:13]
	s_branch .LBB0_603
